# projection phases: every other workgroup (by XCD-local index) starts about 9 us late so the tile epilogue store bursts of the two halves alternate
# speedup vs baseline: 1.0012x; 1.0012x over previous
; __global__ void __launch_bounds__(512, 2) mk_fwd(Args args) {
;     ...
;             const int l = __builtin_amdgcn_readfirstlane((ph - 1) >> 3), s = __builtin_amdgcn_readfirstlane((ph - 1) & 7);
;     ...
;             if (s == 3) mixers_phase(C, l, shm, rep ? REP_SUB : 7);
;     ...
;             if (s == 3) {}
;     ...
;             else {
;                 unsigned char* wl = args.ws + WS_W + (size_t)l * W_LAYER;
;                 pg8::Gemm g; pg8::Sched S; pg8::EpiDesc E;
;                 S.nM = MP / 256; S.G = gridDim.x; S.c = blockIdx.x; S.segs = 1;
;                 E.l = l; E.final_ = 0; E.alpha = 1.f; E.rss_in = C.RSS; E.rss_out = C.RSS;
;                 if (s == 0 || s == 6) { g.A = C.XB; g.lda = DM; g.Bt = (const bf16_t*)(wl + (s == 0 ? W_GU1 : W_GU2)); g.ldb = DM; S.nN = NIN / 256; S.nt_full = DM / 64; E.kind = pg8::EK_SWIGLU; E.rss_in = C.RSS + (size_t)(3 * l + (s == 0 ? 0 : 2)) * MP; }
;                 else if (s == 1 || s == 7) { g.A = C.ACT; g.lda = DFF; g.Bt = (const bf16_t*)(wl + (s == 1 ? W_DN1 : W_DN2)); g.ldb = DFF; S.nN = 4; S.nt_full = DFF / 64; E.kind = pg8::EK_RESID; E.alpha = 0.5f; E.rss_out = C.RSS + (size_t)(3 * l + (s == 1 ? 1 : 3)) * MP; E.final_ = (s == 7 && l == 1); }
;                 else if (s == 2) { g.A = C.XB; g.lda = DM; g.Bt = (const bf16_t*)(wl + W_IN); g.ldb = DM; S.nN = NIN / 256; S.nt_full = DM / 64; E.kind = pg8::EK_PROJ; E.rss_in = C.RSS + (size_t)(3 * l + 1) * MP; }
.LBB0_16:
	v_readlane_b32 s0, v254, 47
	v_readlane_b32 s1, v254, 48
	s_and_b64 vcc, exec, s[0:1]
	s_cbranch_vccz .LBB0_29
	v_readlane_b32 s0, v252, 63
	s_add_i32 s35, s0, -1
	v_readlane_b32 s1, v253, 0
	s_ashr_i32 s0, s35, 3
	v_writelane_b32 v254, s0, 51
	s_and_b32 s34, s35, 7
	s_cmp_lg_u32 s34, 3
	v_writelane_b32 v254, s1, 52
	v_writelane_b32 v254, s72, 53
	s_mov_b64 s[0:1], -1
	s_nop 0
	v_writelane_b32 v254, s73, 54
	v_writelane_b32 v254, s74, 55
	v_writelane_b32 v254, s75, 56
	v_writelane_b32 v254, s76, 57
	v_writelane_b32 v254, s77, 58
	v_writelane_b32 v254, s78, 59
	v_writelane_b32 v254, s79, 60
	v_writelane_b32 v251, s83, 0
	v_writelane_b32 v254, s80, 61
	v_writelane_b32 v251, s84, 1
	v_writelane_b32 v254, s81, 62
	v_writelane_b32 v251, s85, 2
	v_writelane_b32 v254, s82, 63
	v_writelane_b32 v251, s86, 3
	v_writelane_b32 v251, s87, 4
	s_cbranch_scc0 .LBB0_503
	s_cmp_eq_u32 s34, 2
	s_cbranch_scc0 .Lskew_done
	v_readlane_b32 s0, v252, 0
	s_lshr_b32 s0, s0, 3
	s_lshr_b32 s1, s0, 3
	s_add_i32 s0, s0, s1
	s_and_b32 s0, s0, 1
	s_cmp_eq_u32 s0, 0
	s_cbranch_scc1 .Lskew_done
	s_sleep 127
	s_sleep 127
.Lskew_done:
	v_readlane_b32 s0, v254, 51
	v_readlane_b32 s1, v254, 52
	s_mov_b32 s2, s0
	s_mul_i32 s1, s2, 0x3000000
	s_mul_hi_i32 s0, s0, 0x3000000
	s_add_u32 s18, s96, s1
	s_addc_u32 s26, s97, s0
	s_cmp_lt_i32 s34, 4
	s_mov_b64 s[6:7], -1
	s_mov_b64 s[20:21], 0
	s_mov_b64 s[2:3], 0
	s_mov_b64 s[10:11], 0
	s_mov_b64 s[8:9], 0
	s_cbranch_scc1 .LBB0_25
	s_mov_b64 s[0:1], -1
	s_cmp_gt_i32 s34, 5
	s_cbranch_scc0 .LBB0_21
	s_cmp_gt_i32 s34, 6
	s_mov_b64 s[0:1], 0
	s_mov_b64 s[2:3], -1
	s_cselect_b64 s[10:11], -1, 0
